# attention: hh1 QK chains issued back to back (one MFMA drain nop removed), static s_setprio 1 for waves 4-7 in the attention loop
# speedup vs baseline: 1.0138x; 1.0116x over previous
; #define GAS __attribute__((address_space(1)))
; __device__ __forceinline__ unsigned pk2(float lo, float hi) { return cvtpk(lo, hi); }
; __device__ __forceinline__ void attn_unit(LAS unsigned char* lds, const GAS bf16_t* __restrict__ QR, const GAS float* __restrict__ ssq, const GAS float* __restrict__ RT, const GAS bf16_t* __restrict__ K, const GAS bf16_t* __restrict__ Vt, GAS bf16_t* __restrict__ A2, int b, int h, int qb, int tid, i ...
;     ...
;     asm volatile("s_waitcnt lgkmcnt(0)\n\ts_barrier" ::: "memory");
;     {   const float inv = 1.f / (lA + __shfl_xor(lA, 32));
;         GAS bf16_t* op = A2 + (size_t)(b * SEQ + q0 + r32) * DM + 512 + h * 64 + 4 * hi;
; #pragma unroll
;         for (int g = 0; g < 4; ++g) { u32x2 w0, w1; w0.x = pk2(oA0[4 * g] * inv, oA0[4 * g + 1] * inv); w0.y = pk2(oA0[4 * g + 2] * inv, oA0[4 * g + 3] * inv);
;             w1.x = pk2(oA1[4 * g] * inv, oA1[4 * g + 1] * inv); w1.y = pk2(oA1[4 * g + 2] * inv, oA1[4 * g + 3] * inv);
;             *(GAS u32x2*)(op + 8 * g) = w0; *(GAS u32x2*)(op + 32 + 8 * g) = w1; } }
;     {   const float inv = 1.f / (lB + __shfl_xor(lB, 32));
;         GAS bf16_t* op = A2 + (size_t)(b * SEQ + q0 + 32 + r32) * DM + 512 + h * 64 + 4 * hi;
; #pragma unroll
;         for (int g = 0; g < 4; ++g) { u32x2 w0, w1; w0.x = pk2(oB0[4 * g] * inv, oB0[4 * g + 1] * inv); w0.y = pk2(oB0[4 * g + 2] * inv, oB0[4 * g + 3] * inv);
;             w1.x = pk2(oB1[4 * g] * inv, oB1[4 * g + 1] * inv); w1.y = pk2(oB1[4 * g + 2] * inv, oB1[4 * g + 3] * inv);
;             *(GAS u32x2*)(op + 8 * g) = w0; *(GAS u32x2*)(op + 32 + 8 * g) = w1; } }
.LBB0_132:
	s_setprio 0
	ds_bpermute_b32 v1, v153, v211
	s_add_i32 s43, s43, s64
	v_or_b32_e32 v66, s43, v151
	s_lshl_b32 s50, s42, 7
	v_mov_b32_e32 v179, v0
	s_waitcnt lgkmcnt(0)
	v_add_f32_e32 v1, v211, v1
	v_div_scale_f32 v67, s[24:25], v1, v1, 1.0
	v_rcp_f32_e32 v68, v67
	v_div_scale_f32 v69, vcc, 1.0, v1, 1.0
	s_waitcnt lgkmcnt(0)
	s_barrier
	v_fma_f32 v70, -v67, v68, 1.0
	v_fmac_f32_e32 v68, v70, v68
	v_mul_f32_e32 v70, v69, v68
	v_fma_f32 v71, -v67, v70, v69
	v_fmac_f32_e32 v70, v71, v68
	v_fma_f32 v67, -v67, v70, v69
	v_div_fmas_f32 v67, v67, v68, v70
	v_div_fixup_f32 v68, v67, v1, 1.0
	v_ashrrev_i32_e32 v67, 31, v66
	v_lshlrev_b64 v[66:67], 11, v[66:67]
	v_lshl_add_u64 v[66:67], s[86:87], 0, v[66:67]
	ds_bpermute_b32 v1, v153, v209
	v_lshl_add_u64 v[66:67], v[66:67], 0, s[50:51]
	v_pk_mul_f32 v[50:51], v[50:51], v[68:69] op_sel_hi:[1,0]
	v_pk_mul_f32 v[52:53], v[52:53], v[68:69] op_sel_hi:[1,0]
	v_pk_mul_f32 v[34:35], v[34:35], v[68:69] op_sel_hi:[1,0]
	v_pk_mul_f32 v[36:37], v[36:37], v[68:69] op_sel_hi:[1,0]
	v_lshl_add_u64 v[66:67], v[66:67], 0, v[178:179]
	v_cvt_pk_bf16_f32 v50, v50, v51
	v_cvt_pk_bf16_f32 v51, v52, v53
	v_cvt_pk_bf16_f32 v34, v34, v35
	v_cvt_pk_bf16_f32 v35, v36, v37
	global_store_dwordx2 v[66:67], v[50:51], off offset:1024
	global_store_dwordx2 v[66:67], v[34:35], off offset:1088
	v_pk_mul_f32 v[34:35], v[54:55], v[68:69] op_sel_hi:[1,0]
	v_pk_mul_f32 v[36:37], v[56:57], v[68:69] op_sel_hi:[1,0]
	v_cvt_pk_bf16_f32 v34, v34, v35
	v_cvt_pk_bf16_f32 v35, v36, v37
	v_pk_mul_f32 v[36:37], v[38:39], v[68:69] op_sel_hi:[1,0]
	v_pk_mul_f32 v[38:39], v[40:41], v[68:69] op_sel_hi:[1,0]
	v_cvt_pk_bf16_f32 v36, v36, v37
	v_cvt_pk_bf16_f32 v37, v38, v39
	s_waitcnt lgkmcnt(0)
	v_add_f32_e32 v1, v209, v1
	global_store_dwordx2 v[66:67], v[34:35], off offset:1040
	global_store_dwordx2 v[66:67], v[36:37], off offset:1104
	v_pk_mul_f32 v[34:35], v[58:59], v[68:69] op_sel_hi:[1,0]
	v_pk_mul_f32 v[36:37], v[60:61], v[68:69] op_sel_hi:[1,0]
	v_div_scale_f32 v40, s[24:25], v1, v1, 1.0
	v_cvt_pk_bf16_f32 v34, v34, v35
	v_cvt_pk_bf16_f32 v35, v36, v37
	v_pk_mul_f32 v[36:37], v[42:43], v[68:69] op_sel_hi:[1,0]
	v_pk_mul_f32 v[38:39], v[44:45], v[68:69] op_sel_hi:[1,0]
	v_rcp_f32_e32 v41, v40
	v_cvt_pk_bf16_f32 v36, v36, v37
	v_cvt_pk_bf16_f32 v37, v38, v39
	global_store_dwordx2 v[66:67], v[34:35], off offset:1056
	global_store_dwordx2 v[66:67], v[36:37], off offset:1120
	v_pk_mul_f32 v[34:35], v[62:63], v[68:69] op_sel_hi:[1,0]
	v_pk_mul_f32 v[36:37], v[64:65], v[68:69] op_sel_hi:[1,0]
	v_cvt_pk_bf16_f32 v34, v34, v35
	v_cvt_pk_bf16_f32 v35, v36, v37
	v_pk_mul_f32 v[36:37], v[46:47], v[68:69] op_sel_hi:[1,0]
	v_pk_mul_f32 v[38:39], v[48:49], v[68:69] op_sel_hi:[1,0]
	v_cvt_pk_bf16_f32 v36, v36, v37
	v_cvt_pk_bf16_f32 v37, v38, v39
	global_store_dwordx2 v[66:67], v[34:35], off offset:1072
	global_store_dwordx2 v[66:67], v[36:37], off offset:1136
	v_fma_f32 v34, -v40, v41, 1.0
	v_fmac_f32_e32 v41, v34, v41
	v_div_scale_f32 v34, vcc, 1.0, v1, 1.0
	v_mul_f32_e32 v35, v34, v41
	v_fma_f32 v36, -v40, v35, v34
	v_fmac_f32_e32 v35, v36, v41
	v_or_b32_e32 v36, s43, v208
	v_fma_f32 v34, -v40, v35, v34
	v_ashrrev_i32_e32 v37, 31, v36
	v_div_fmas_f32 v34, v34, v41, v35
	v_lshlrev_b64 v[36:37], 11, v[36:37]
	v_div_fixup_f32 v34, v34, v1, 1.0
	v_lshl_add_u64 v[36:37], s[86:87], 0, v[36:37]
	v_lshl_add_u64 v[36:37], v[36:37], 0, s[50:51]
	v_pk_mul_f32 v[18:19], v[18:19], v[34:35] op_sel_hi:[1,0]
	v_pk_mul_f32 v[20:21], v[20:21], v[34:35] op_sel_hi:[1,0]
	v_pk_mul_f32 v[2:3], v[2:3], v[34:35] op_sel_hi:[1,0]
	v_pk_mul_f32 v[4:5], v[4:5], v[34:35] op_sel_hi:[1,0]
	v_lshl_add_u64 v[36:37], v[36:37], 0, v[178:179]
	v_cvt_pk_bf16_f32 v18, v18, v19
	v_cvt_pk_bf16_f32 v19, v20, v21
	v_cvt_pk_bf16_f32 v2, v2, v3
	v_cvt_pk_bf16_f32 v3, v4, v5
	global_store_dwordx2 v[36:37], v[18:19], off offset:1024
	global_store_dwordx2 v[36:37], v[2:3], off offset:1088
	v_pk_mul_f32 v[2:3], v[22:23], v[34:35] op_sel_hi:[1,0]
	v_pk_mul_f32 v[4:5], v[24:25], v[34:35] op_sel_hi:[1,0]
	v_cvt_pk_bf16_f32 v2, v2, v3
	v_cvt_pk_bf16_f32 v3, v4, v5
	v_pk_mul_f32 v[4:5], v[6:7], v[34:35] op_sel_hi:[1,0]
	v_pk_mul_f32 v[6:7], v[8:9], v[34:35] op_sel_hi:[1,0]
	v_cvt_pk_bf16_f32 v4, v4, v5
	v_cvt_pk_bf16_f32 v5, v6, v7
	global_store_dwordx2 v[36:37], v[2:3], off offset:1040
	global_store_dwordx2 v[36:37], v[4:5], off offset:1104
	v_pk_mul_f32 v[2:3], v[26:27], v[34:35] op_sel_hi:[1,0]
	v_pk_mul_f32 v[4:5], v[28:29], v[34:35] op_sel_hi:[1,0]
	v_cvt_pk_bf16_f32 v2, v2, v3
	v_cvt_pk_bf16_f32 v3, v4, v5
	v_pk_mul_f32 v[4:5], v[10:11], v[34:35] op_sel_hi:[1,0]
	v_pk_mul_f32 v[6:7], v[12:13], v[34:35] op_sel_hi:[1,0]
	v_cvt_pk_bf16_f32 v4, v4, v5
	v_cvt_pk_bf16_f32 v5, v6, v7
	global_store_dwordx2 v[36:37], v[2:3], off offset:1056
	global_store_dwordx2 v[36:37], v[4:5], off offset:1120
	v_pk_mul_f32 v[2:3], v[30:31], v[34:35] op_sel_hi:[1,0]
	v_pk_mul_f32 v[4:5], v[32:33], v[34:35] op_sel_hi:[1,0]
	v_cvt_pk_bf16_f32 v2, v2, v3
	v_cvt_pk_bf16_f32 v3, v4, v5
	v_pk_mul_f32 v[4:5], v[14:15], v[34:35] op_sel_hi:[1,0]
	v_pk_mul_f32 v[6:7], v[16:17], v[34:35] op_sel_hi:[1,0]
	s_add_i32 s17, s17, 1
	v_cvt_pk_bf16_f32 v4, v4, v5
	v_cvt_pk_bf16_f32 v5, v6, v7
	s_cmp_ge_i32 s17, s19
	global_store_dwordx2 v[36:37], v[2:3], off offset:1072
	global_store_dwordx2 v[36:37], v[4:5], off offset:1136
	s_cbranch_scc1 .LBB0_149
; #define GAS __attribute__((address_space(1)))
; __device__ __forceinline__ unsigned pk2(float lo, float hi) { return cvtpk(lo, hi); }
; __device__ __forceinline__ float bflo(unsigned w) { return __uint_as_float(w << 16); }
; __device__ __forceinline__ float bfhi(unsigned w) { return __uint_as_float(w & 0xffff0000u); }
; __device__ __forceinline__ void attn_unit(LAS unsigned char* lds, const GAS bf16_t* __restrict__ QR, const GAS float* __restrict__ ssq, const GAS float* __restrict__ RT, const GAS bf16_t* __restrict__ K, const GAS bf16_t* __restrict__ Vt, GAS bf16_t* __restrict__ A2, int b, int h, int qb, int tid, i ...
;     const int r32 = lane & 31, hi = lane >> 5, q0 = qb * 512 + wave * 64, r32s = (r32 & ~12) | ((r32 & 4) << 1) | ((r32 & 8) >> 1);
;     bf16x8 qa[6], qc[6];
; #pragma unroll
;     for (int sub = 0; sub < 2; ++sub) {
;         const int s = q0 + 32 * sub + r32, row = b * SEQ + s;
;         const GAS bf16_t* Qp = QR + (size_t)row * 768 + h * 96 + 8 * hi;
;         const float sc = rsqrtf(ssq[row] * (1.f / 256.f) + EPS) * QSCALE;
; #pragma unroll
;         for (int d0 = 0; d0 < 6; ++d0) {
;             const u32x4 raw = *(const GAS u32x4*)(Qp + 16 * d0);
;             float v[8];
; #pragma unroll
;             for (int j = 0; j < 4; ++j) { v[2 * j] = bflo(raw[j]) * sc; v[2 * j + 1] = bfhi(raw[j]) * sc; }
;             if (d0 >= 4) { const GAS float* rt = RT + (d0 == 4 ? (s >> 6) : (s & 63)) * 16;
; #pragma unroll
;                 for (int j = 0; j < 8; ++j) { const float pt = __shfl_xor(v[j], 32), cs = rt[2 * j], sn = rt[2 * j + 1]; v[j] = hi ? v[j] * cs + pt * sn : v[j] * cs - pt * sn; } }
;             u32x4 w; w.x = pk2(v[0], v[1]); w.y = pk2(v[2], v[3]); w.z = pk2(v[4], v[5]); w.w = pk2(v[6], v[7]);
;             if (sub == 0) qa[d0] = __builtin_bit_cast(bf16x8, w); else qc[d0] = __builtin_bit_cast(bf16x8, w);
;         }
;     }
.LBB0_133:
	s_lshl_b32 s22, s17, 9
	s_and_b32 s43, s22, 0x1e00
	s_ashr_i32 s1, s17, 7
	s_add_i32 s43, s43, s65
	s_bfe_u32 s42, s17, 0x30004
	v_or_b32_e32 v1, s43, v151
	s_lshl_b32 s64, s1, 13
	s_mul_i32 s50, s42, 0xc0
	v_add_u32_e32 v2, s64, v1
	v_lshl_add_u64 v[6:7], v[156:157], 0, s[50:51]
	s_movk_i32 s22, 0x600
	v_ashrrev_i32_e32 v3, 31, v2
	v_mad_i64_i32 v[8:9], s[24:25], v2, s22, v[6:7]
	v_lshl_add_u64 v[2:3], v[2:3], 2, s[78:79]
	global_load_dwordx4 v[10:13], v[8:9], off
	global_load_dwordx4 v[18:21], v[8:9], off offset:32
	global_load_dwordx4 v[34:37], v[8:9], off offset:64
	global_load_dwordx4 v[38:41], v[8:9], off offset:96
	global_load_dword v64, v[2:3], off
	v_or_b32_e32 v1, 32, v1
	v_add_u32_e32 v30, s64, v1
	v_ashrrev_i32_e32 v31, 31, v30
	v_mad_i64_i32 v[32:33], s[24:25], v30, s22, v[6:7]
	v_lshl_add_u64 v[30:31], v[30:31], 2, s[78:79]
	global_load_dwordx4 v[14:17], v[158:159], off offset:48
	global_load_dwordx4 v[22:25], v[158:159], off offset:32
	global_load_dwordx4 v[26:29], v[158:159], off offset:16
	global_load_dwordx4 v[42:45], v[158:159], off
	global_load_dwordx4 v[2:5], v[8:9], off offset:128
	global_load_dwordx4 v[46:49], v[8:9], off offset:160
	s_nop 0
	global_load_dwordx4 v[6:9], v[32:33], off
	s_nop 0
	global_load_dword v31, v[30:31], off
	s_ashr_i32 s24, s43, 2
	s_ashr_i32 s25, s24, 31
	s_lshl_b64 s[24:25], s[24:25], 2
	s_add_u32 s56, s34, s24
	s_addc_u32 s57, s35, s25
	v_lshlrev_b32_e32 v1, 6, v1
	v_and_b32_e32 v1, 0xfc0, v1
	s_lshl_b32 s1, s1, 3
	s_or_b32 s1, s1, s42
	s_mul_i32 s23, s1, 0x18c000
	s_mul_hi_i32 s22, s1, 0x18c000
	s_add_u32 s24, s84, s23
	s_addc_u32 s25, s85, s22
	s_mul_hi_i32 s22, s1, 0x108000
	s_mul_i32 s1, s1, 0x108000
	s_add_u32 s26, s82, s1
	s_addc_u32 s27, s83, s22
	s_mov_b32 s50, 2
	s_mov_b32 s49, 0
	v_mov_b32_e32 v179, 0xf149f2ca
	v_mov_b32_e32 v211, 0
	v_mov_b32_e32 v209, 0
	s_waitcnt vmcnt(12)
	v_lshlrev_b32_e32 v50, 16, v10
	v_and_b32_e32 v51, 0xffff0000, v10
	v_lshlrev_b32_e32 v10, 16, v11
	s_waitcnt vmcnt(9)
	v_and_b32_e32 v65, 0xffff0000, v40
	s_waitcnt vmcnt(8)
	v_fmamk_f32 v30, v64, 0x3b800000, v146
	v_mul_f32_e32 v64, 0x4b800000, v30
	v_cmp_gt_f32_e32 vcc, s14, v30
	v_and_b32_e32 v11, 0xffff0000, v11
	v_lshlrev_b32_e32 v54, 16, v18
	v_cndmask_b32_e32 v30, v30, v64, vcc
	v_rsq_f32_e32 v30, v30
	v_lshlrev_b32_e32 v64, 16, v40
	v_and_b32_e32 v55, 0xffff0000, v18
	v_lshlrev_b32_e32 v18, 16, v19
	v_mul_f32_e32 v40, 0x45800000, v30
	v_cndmask_b32_e32 v30, v30, v40, vcc
	v_mul_f32_e32 v30, 0x3e16c740, v30
	s_waitcnt vmcnt(0)
	v_pk_mul_f32 v[10:11], v[30:31], v[10:11] op_sel_hi:[0,1]
	v_cvt_pk_bf16_f32 v99, v10, v11
	v_lshlrev_b32_e32 v10, 16, v41
	v_and_b32_e32 v11, 0xffff0000, v41
	v_and_b32_e32 v19, 0xffff0000, v19
	v_pk_mul_f32 v[10:11], v[30:31], v[10:11] op_sel_hi:[0,1]
	v_lshlrev_b32_e32 v56, 16, v20
	v_and_b32_e32 v57, 0xffff0000, v20
	v_lshlrev_b32_e32 v20, 16, v21
	v_and_b32_e32 v21, 0xffff0000, v21
	v_pk_mul_f32 v[18:19], v[30:31], v[18:19] op_sel_hi:[0,1]
	v_cvt_pk_bf16_f32 v113, v10, v11
	v_lshlrev_b32_e32 v10, 16, v46
	v_and_b32_e32 v11, 0xffff0000, v46
	v_pk_mul_f32 v[20:21], v[30:31], v[20:21] op_sel_hi:[0,1]
	v_cvt_pk_bf16_f32 v103, v18, v19
	v_pk_mul_f32 v[18:19], v[30:31], v[10:11] op_sel_hi:[0,1]
	v_cvt_pk_bf16_f32 v105, v20, v21
	ds_bpermute_b32 v20, v153, v18
	ds_bpermute_b32 v21, v153, v19
	v_lshlrev_b32_e32 v58, 16, v34
	v_and_b32_e32 v59, 0xffff0000, v34
	v_lshlrev_b32_e32 v34, 16, v35
	v_and_b32_e32 v35, 0xffff0000, v35
	v_pk_mul_f32 v[34:35], v[30:31], v[34:35] op_sel_hi:[0,1]
	v_cvt_pk_bf16_f32 v107, v34, v35
	v_mov_b32_e32 v35, v44
	v_mov_b32_e32 v44, v43
	s_waitcnt lgkmcnt(0)
	v_pk_mul_f32 v[20:21], v[44:45], v[20:21]
	v_lshlrev_b32_e32 v60, 16, v36
	v_and_b32_e32 v61, 0xffff0000, v36
	v_lshlrev_b32_e32 v36, 16, v37
	v_and_b32_e32 v37, 0xffff0000, v37
	v_mov_b32_e32 v34, v42
	v_cndmask_b32_e64 v21, v21, -v21, s[6:7]
	v_cndmask_b32_e64 v20, v20, -v20, s[6:7]
	v_lshlrev_b32_e32 v52, 16, v12
	v_and_b32_e32 v53, 0xffff0000, v12
	v_lshlrev_b32_e32 v12, 16, v13
	v_and_b32_e32 v13, 0xffff0000, v13
	v_lshlrev_b32_e32 v62, 16, v38
	v_and_b32_e32 v63, 0xffff0000, v38
	v_lshlrev_b32_e32 v38, 16, v39
	v_and_b32_e32 v39, 0xffff0000, v39
	v_pk_mul_f32 v[36:37], v[30:31], v[36:37] op_sel_hi:[0,1]
	v_pk_fma_f32 v[34:35], v[18:19], v[34:35], v[20:21]
	v_lshlrev_b32_e32 v18, 16, v47
	v_and_b32_e32 v19, 0xffff0000, v47
	v_pk_mul_f32 v[12:13], v[30:31], v[12:13] op_sel_hi:[0,1]
	v_pk_mul_f32 v[38:39], v[30:31], v[38:39] op_sel_hi:[0,1]
	v_cvt_pk_bf16_f32 v109, v36, v37
	v_pk_mul_f32 v[36:37], v[30:31], v[18:19] op_sel_hi:[0,1]
	v_cvt_pk_bf16_f32 v101, v12, v13
	v_cvt_pk_bf16_f32 v111, v38, v39
	global_load_dwordx4 v[10:13], v[32:33], off offset:32
	global_load_dwordx4 v[18:21], v[32:33], off offset:64
	ds_bpermute_b32 v38, v153, v36
	ds_bpermute_b32 v39, v153, v37
	v_mov_b32_e32 v41, v28
	v_mov_b32_e32 v28, v27
	v_mov_b32_e32 v40, v26
	v_pk_mul_f32 v[50:51], v[30:31], v[50:51] op_sel_hi:[0,1]
	s_waitcnt lgkmcnt(0)
	v_pk_mul_f32 v[26:27], v[28:29], v[38:39]
	v_lshlrev_b32_e32 v28, 16, v48
	v_and_b32_e32 v29, 0xffff0000, v48
	v_pk_mul_f32 v[28:29], v[30:31], v[28:29] op_sel_hi:[0,1]
	v_cndmask_b32_e64 v27, v27, -v27, s[6:7]
	v_cndmask_b32_e64 v26, v26, -v26, s[6:7]
	ds_bpermute_b32 v38, v153, v28
	ds_bpermute_b32 v39, v153, v29
	v_pk_fma_f32 v[26:27], v[36:37], v[40:41], v[26:27]
	v_lshlrev_b32_e32 v40, 16, v49
	v_and_b32_e32 v41, 0xffff0000, v49
	v_pk_mul_f32 v[40:41], v[30:31], v[40:41] op_sel_hi:[0,1]
	ds_bpermute_b32 v42, v153, v40
	ds_bpermute_b32 v43, v153, v41
	v_mov_b32_e32 v37, v24
	v_mov_b32_e32 v24, v23
	v_mov_b32_e32 v36, v22
	s_waitcnt lgkmcnt(2)
; #define GAS __attribute__((address_space(1)))
; __device__ __forceinline__ unsigned pk2(float lo, float hi) { return cvtpk(lo, hi); }
; __device__ __forceinline__ float bflo(unsigned w) { return __uint_as_float(w << 16); }
; __device__ __forceinline__ float bfhi(unsigned w) { return __uint_as_float(w & 0xffff0000u); }
; __device__ __forceinline__ void attn_unit(LAS unsigned char* lds, const GAS bf16_t* __restrict__ QR, const GAS float* __restrict__ ssq, const GAS float* __restrict__ RT, const GAS bf16_t* __restrict__ K, const GAS bf16_t* __restrict__ Vt, GAS bf16_t* __restrict__ A2, int b, int h, int qb, int tid, i ...
;     ...
;     for (int sub = 0; sub < 2; ++sub) {
;         const int s = q0 + 32 * sub + r32, row = b * SEQ + s;
;         const GAS bf16_t* Qp = QR + (size_t)row * 768 + h * 96 + 8 * hi;
;         const float sc = rsqrtf(ssq[row] * (1.f / 256.f) + EPS) * QSCALE;
; #pragma unroll
;         for (int d0 = 0; d0 < 6; ++d0) {
;             const u32x4 raw = *(const GAS u32x4*)(Qp + 16 * d0);
;             float v[8];
; #pragma unroll
;             for (int j = 0; j < 4; ++j) { v[2 * j] = bflo(raw[j]) * sc; v[2 * j + 1] = bfhi(raw[j]) * sc; }
;             if (d0 >= 4) { const GAS float* rt = RT + (d0 == 4 ? (s >> 6) : (s & 63)) * 16;
; #pragma unroll
;                 for (int j = 0; j < 8; ++j) { const float pt = __shfl_xor(v[j], 32), cs = rt[2 * j], sn = rt[2 * j + 1]; v[j] = hi ? v[j] * cs + pt * sn : v[j] * cs - pt * sn; } }
;             u32x4 w; w.x = pk2(v[0], v[1]); w.y = pk2(v[2], v[3]); w.z = pk2(v[4], v[5]); w.w = pk2(v[6], v[7]);
;             if (sub == 0) qa[d0] = __builtin_bit_cast(bf16x8, w); else qc[d0] = __builtin_bit_cast(bf16x8, w);
;         }
	v_pk_mul_f32 v[22:23], v[24:25], v[38:39]
	v_pk_mul_f32 v[52:53], v[30:31], v[52:53] op_sel_hi:[0,1]
	v_cndmask_b32_e64 v39, v23, -v23, s[6:7]
	v_cndmask_b32_e64 v38, v22, -v22, s[6:7]
	global_load_dwordx4 v[22:25], v[32:33], off offset:96
	v_pk_fma_f32 v[38:39], v[28:29], v[36:37], v[38:39]
	v_mov_b32_e32 v29, v16
	v_mov_b32_e32 v16, v15
	v_mov_b32_e32 v28, v14
	s_waitcnt lgkmcnt(0)
	v_pk_mul_f32 v[14:15], v[16:17], v[42:43]
	v_pk_mul_f32 v[54:55], v[30:31], v[54:55] op_sel_hi:[0,1]
	v_pk_mul_f32 v[56:57], v[30:31], v[56:57] op_sel_hi:[0,1]
	v_pk_mul_f32 v[58:59], v[30:31], v[58:59] op_sel_hi:[0,1]
	v_pk_mul_f32 v[60:61], v[30:31], v[60:61] op_sel_hi:[0,1]
	v_pk_mul_f32 v[62:63], v[30:31], v[62:63] op_sel_hi:[0,1]
	v_pk_mul_f32 v[64:65], v[30:31], v[64:65] op_sel_hi:[0,1]
	v_cndmask_b32_e64 v15, v15, -v15, s[6:7]
	v_cndmask_b32_e64 v14, v14, -v14, s[6:7]
	v_fmamk_f32 v31, v31, 0x3b800000, v146
	v_pk_fma_f32 v[42:43], v[40:41], v[28:29], v[14:15]
	v_mul_f32_e32 v40, 0x4b800000, v31
	v_cmp_gt_f32_e32 vcc, s14, v31
	v_cvt_pk_bf16_f32 v114, v34, v35
	v_cvt_pk_bf16_f32 v115, v26, v27
	global_load_dwordx4 v[14:17], v[32:33], off offset:160
	global_load_dwordx4 v[26:29], v0, s[56:57] offset:16
	global_load_dwordx4 v[34:37], v0, s[56:57]
	v_cndmask_b32_e32 v31, v31, v40, vcc
	v_cvt_pk_bf16_f32 v116, v38, v39
	global_load_dwordx4 v[38:41], v[32:33], off offset:128
	v_rsq_f32_e32 v31, v31
	v_cvt_pk_bf16_f32 v117, v42, v43
	v_and_b32_e32 v33, 0xffff0000, v6
	v_lshlrev_b32_e32 v44, 16, v8
	v_mul_f32_e32 v32, 0x45800000, v31
	v_cndmask_b32_e32 v31, v31, v32, vcc
	v_mul_f32_e32 v42, 0x3e16c740, v31
	v_lshlrev_b32_e32 v32, 16, v6
	v_lshlrev_b32_e32 v6, 16, v7
	v_and_b32_e32 v7, 0xffff0000, v7
	v_pk_mul_f32 v[6:7], v[42:43], v[6:7] op_sel_hi:[0,1]
	v_and_b32_e32 v45, 0xffff0000, v8
	v_lshlrev_b32_e32 v8, 16, v9
	v_and_b32_e32 v9, 0xffff0000, v9
	v_cvt_pk_bf16_f32 v119, v6, v7
	v_pk_mul_f32 v[8:9], v[42:43], v[8:9] op_sel_hi:[0,1]
	v_pk_mul_f32 v[32:33], v[42:43], v[32:33] op_sel_hi:[0,1]
	v_cvt_pk_bf16_f32 v121, v8, v9
	v_cvt_pk_bf16_f32 v118, v32, v33
	v_pk_mul_f32 v[44:45], v[42:43], v[44:45] op_sel_hi:[0,1]
	v_cvt_pk_bf16_f32 v120, v44, v45
	v_cvt_pk_bf16_f32 v98, v50, v51
	v_cvt_pk_bf16_f32 v100, v52, v53
	v_cvt_pk_bf16_f32 v102, v54, v55
	v_cvt_pk_bf16_f32 v104, v56, v57
	v_cvt_pk_bf16_f32 v106, v58, v59
	s_waitcnt vmcnt(6)
	v_lshlrev_b32_e32 v6, 16, v10
	v_and_b32_e32 v7, 0xffff0000, v10
	v_pk_mul_f32 v[6:7], v[42:43], v[6:7] op_sel_hi:[0,1]
	v_lshlrev_b32_e32 v8, 16, v11
	v_and_b32_e32 v9, 0xffff0000, v11
	v_lshlrev_b32_e32 v10, 16, v12
	v_and_b32_e32 v11, 0xffff0000, v12
	v_lshlrev_b32_e32 v12, 16, v13
	v_and_b32_e32 v13, 0xffff0000, v13
	v_cvt_pk_bf16_f32 v122, v6, v7
	s_waitcnt vmcnt(5)
	v_lshlrev_b32_e32 v6, 16, v18
	v_and_b32_e32 v7, 0xffff0000, v18
	v_pk_mul_f32 v[8:9], v[42:43], v[8:9] op_sel_hi:[0,1]
	v_pk_mul_f32 v[10:11], v[42:43], v[10:11] op_sel_hi:[0,1]
	v_pk_mul_f32 v[12:13], v[42:43], v[12:13] op_sel_hi:[0,1]
	v_pk_mul_f32 v[32:33], v[42:43], v[6:7] op_sel_hi:[0,1]
	v_lshlrev_b32_e32 v6, 16, v19
	v_and_b32_e32 v7, 0xffff0000, v19
	v_cvt_pk_bf16_f32 v123, v8, v9
	v_cvt_pk_bf16_f32 v124, v10, v11
	v_cvt_pk_bf16_f32 v125, v12, v13
	v_pk_mul_f32 v[18:19], v[42:43], v[6:7] op_sel_hi:[0,1]
	global_load_dwordx4 v[6:9], v0, s[56:57] offset:48
	global_load_dwordx4 v[10:13], v0, s[56:57] offset:32
	v_lshlrev_b32_e32 v44, 16, v20
	v_and_b32_e32 v45, 0xffff0000, v20
	v_lshlrev_b32_e32 v20, 16, v21
	v_and_b32_e32 v21, 0xffff0000, v21
	v_cvt_pk_bf16_f32 v127, v18, v19
	v_pk_mul_f32 v[20:21], v[42:43], v[20:21] op_sel_hi:[0,1]
	s_waitcnt vmcnt(6)
	v_lshlrev_b32_e32 v18, 16, v22
	v_and_b32_e32 v19, 0xffff0000, v22
	v_pk_mul_f32 v[18:19], v[42:43], v[18:19] op_sel_hi:[0,1]
	v_cvt_pk_bf16_f32 v129, v20, v21
	v_lshlrev_b32_e32 v20, 16, v23
	v_and_b32_e32 v21, 0xffff0000, v23
	v_cvt_pk_bf16_f32 v130, v18, v19
	v_lshlrev_b32_e32 v18, 16, v2
	v_and_b32_e32 v19, 0xffff0000, v2
	v_pk_mul_f32 v[20:21], v[42:43], v[20:21] op_sel_hi:[0,1]
	v_lshlrev_b32_e32 v22, 16, v24
	v_and_b32_e32 v23, 0xffff0000, v24
	v_pk_mul_f32 v[18:19], v[30:31], v[18:19] op_sel_hi:[0,1]
	v_pk_mul_f32 v[22:23], v[42:43], v[22:23] op_sel_hi:[0,1]
	v_cvt_pk_bf16_f32 v131, v20, v21
	ds_bpermute_b32 v20, v153, v18
	ds_bpermute_b32 v21, v153, v19
	v_cvt_pk_bf16_f32 v132, v22, v23
	v_cvt_pk_bf16_f32 v126, v32, v33
	v_lshlrev_b32_e32 v24, 16, v25
	v_and_b32_e32 v25, 0xffff0000, v25
	s_waitcnt vmcnt(3)
	v_mov_b32_e32 v32, v34
	v_mov_b32_e32 v33, v36
	v_mov_b32_e32 v36, v35
	s_waitcnt vmcnt(2)
	v_lshlrev_b32_e32 v22, 16, v38
	v_and_b32_e32 v23, 0xffff0000, v38
	v_pk_mul_f32 v[34:35], v[42:43], v[22:23] op_sel_hi:[0,1]
	ds_bpermute_b32 v22, v153, v34
	ds_bpermute_b32 v23, v153, v35
	s_waitcnt lgkmcnt(2)
	v_pk_mul_f32 v[20:21], v[36:37], v[20:21]
	v_pk_mul_f32 v[24:25], v[42:43], v[24:25] op_sel_hi:[0,1]
	v_cndmask_b32_e64 v21, v21, -v21, s[6:7]
	v_cndmask_b32_e64 v20, v20, -v20, s[6:7]
	v_pk_fma_f32 v[18:19], v[18:19], v[32:33], v[20:21]
	v_cvt_pk_bf16_f32 v133, v24, v25
	v_cvt_pk_bf16_f32 v134, v18, v19
	s_waitcnt lgkmcnt(0)
	v_pk_mul_f32 v[36:37], v[36:37], v[22:23]
	global_load_dwordx4 v[18:21], v1, s[34:35] offset:16
	global_load_dwordx4 v[22:25], v1, s[34:35]
	v_lshlrev_b32_e32 v2, 16, v3
	v_and_b32_e32 v3, 0xffff0000, v3
	v_pk_mul_f32 v[44:45], v[42:43], v[44:45] op_sel_hi:[0,1]
	v_pk_mul_f32 v[2:3], v[30:31], v[2:3] op_sel_hi:[0,1]
	v_cvt_pk_bf16_f32 v128, v44, v45
	v_cndmask_b32_e64 v37, v37, -v37, s[6:7]
	v_cndmask_b32_e64 v36, v36, -v36, s[6:7]
	ds_bpermute_b32 v44, v153, v2
	ds_bpermute_b32 v45, v153, v3
	v_pk_fma_f32 v[36:37], v[32:33], v[34:35], v[36:37]
	v_lshlrev_b32_e32 v32, 16, v39
	v_and_b32_e32 v33, 0xffff0000, v39
	v_pk_mul_f32 v[38:39], v[42:43], v[32:33] op_sel_hi:[0,1]
	ds_bpermute_b32 v32, v153, v38
	ds_bpermute_b32 v33, v153, v39
	v_mov_b32_e32 v47, v28
	v_mov_b32_e32 v28, v27
	v_mov_b32_e32 v46, v26
	s_waitcnt lgkmcnt(2)
; #define GAS __attribute__((address_space(1)))
; __device__ __forceinline__ unsigned pk2(float lo, float hi) { return cvtpk(lo, hi); }
; #define AT_ISSUE(t, slot) do { _Pragma("unroll") for (int k_ = 0; k_ < 3; ++k_) glds16(src[k_] + (size_t)(t) * stride[k_], (unsigned)__builtin_amdgcn_readfirstlane(dsto[k_] + (slot) * AT_SLOT)); } while (0)
; __device__ __forceinline__ void attn_unit(LAS unsigned char* lds, const GAS bf16_t* __restrict__ QR, const GAS float* __restrict__ ssq, const GAS float* __restrict__ RT, const GAS bf16_t* __restrict__ K, const GAS bf16_t* __restrict__ Vt, GAS bf16_t* __restrict__ A2, int b, int h, int qb, int tid, i ...
;     ...
;             if (d0 >= 4) { const GAS float* rt = RT + (d0 == 4 ? (s >> 6) : (s & 63)) * 16;
; #pragma unroll
;                 for (int j = 0; j < 8; ++j) { const float pt = __shfl_xor(v[j], 32), cs = rt[2 * j], sn = rt[2 * j + 1]; v[j] = hi ? v[j] * cs + pt * sn : v[j] * cs - pt * sn; } }
;             u32x4 w; w.x = pk2(v[0], v[1]); w.y = pk2(v[2], v[3]); w.z = pk2(v[4], v[5]); w.w = pk2(v[6], v[7]);
;             if (sub == 0) qa[d0] = __builtin_bit_cast(bf16x8, w); else qc[d0] = __builtin_bit_cast(bf16x8, w);
;         }
;     }
;     const GAS unsigned char* Kg = (const GAS unsigned char*)(K + (size_t)(b * 8 + h) * KVLEN * 96);
;     const GAS unsigned char* Vg = (const GAS unsigned char*)(Vt + (size_t)(b * 8 + h) * 64 * KVLEN);
;     const unsigned ldsb = (unsigned)(size_t)lds;
;     const GAS unsigned char* src[3]; int stride[3]; unsigned dsto[3];
; #pragma unroll
;     for (int k = 0; k < 3; ++k) { int j = wave + 8 * k; if (j >= AT_NP) j -= 8; const int id = j * 64 + lane;
;         if (j < 13) { const int row = id / 13; int col = id - row * 13; if (col == 12) col = 0; src[k] = Kg + row * 192 + col * 16; stride[k] = 12288; }
;         else { const int idv = id - 832, d = idv / 9; int c = idv - d * 9; if (c == 8) c = 0; src[k] = Vg + ((size_t)d * KVLEN + c * 8) * 2; stride[k] = 128; }
;         dsto[k] = ldsb + j * 1024; }
;     ...
;     f32x16 oA0, oA1, oB0, oB1;
; #pragma unroll
;     for (int i = 0; i < 16; ++i) { oA0[i] = 0.f; oA1[i] = 0.f; oB0[i] = 0.f; oB1[i] = 0.f; }
;     float mA = -1e30f, mB = -1e30f, lA = 0.f, lB = 0.f;
;     constexpr int NT_ = KVLEN / 64;
;     AT_ISSUE(0, 0); AT_ISSUE(1, 1);
	v_pk_mul_f32 v[26:27], v[28:29], v[44:45]
	v_lshlrev_b32_e32 v44, 16, v4
	v_cndmask_b32_e64 v27, v27, -v27, s[6:7]
	v_cndmask_b32_e64 v26, v26, -v26, s[6:7]
	v_pk_fma_f32 v[2:3], v[2:3], v[46:47], v[26:27]
	v_and_b32_e32 v45, 0xffff0000, v4
	v_cvt_pk_bf16_f32 v135, v2, v3
	s_waitcnt lgkmcnt(0)
	v_pk_mul_f32 v[2:3], v[28:29], v[32:33]
	global_load_dwordx4 v[26:29], v1, s[34:35] offset:48
	global_load_dwordx4 v[32:35], v1, s[34:35] offset:32
	v_pk_mul_f32 v[44:45], v[30:31], v[44:45] op_sel_hi:[0,1]
	ds_bpermute_b32 v48, v153, v44
	ds_bpermute_b32 v49, v153, v45
	v_cndmask_b32_e64 v3, v3, -v3, s[6:7]
	v_cndmask_b32_e64 v2, v2, -v2, s[6:7]
	v_pk_fma_f32 v[2:3], v[46:47], v[38:39], v[2:3]
	v_lshlrev_b32_e32 v46, 16, v40
	v_and_b32_e32 v47, 0xffff0000, v40
	s_waitcnt vmcnt(4)
	v_mov_b32_e32 v39, v12
	v_mov_b32_e32 v12, v11
	v_pk_mul_f32 v[46:47], v[42:43], v[46:47] op_sel_hi:[0,1]
	v_mov_b32_e32 v38, v10
	s_waitcnt lgkmcnt(0)
	v_pk_mul_f32 v[10:11], v[12:13], v[48:49]
	ds_bpermute_b32 v48, v153, v46
	ds_bpermute_b32 v49, v153, v47
	v_cndmask_b32_e64 v11, v11, -v11, s[6:7]
	v_cndmask_b32_e64 v10, v10, -v10, s[6:7]
	v_lshlrev_b32_e32 v4, 16, v5
	v_and_b32_e32 v5, 0xffff0000, v5
	v_pk_fma_f32 v[10:11], v[44:45], v[38:39], v[10:11]
	v_pk_mul_f32 v[4:5], v[30:31], v[4:5] op_sel_hi:[0,1]
	v_cvt_pk_bf16_f32 v136, v10, v11
	s_waitcnt lgkmcnt(0)
	v_pk_mul_f32 v[10:11], v[12:13], v[48:49]
	ds_bpermute_b32 v12, v153, v4
	ds_bpermute_b32 v13, v153, v5
	v_mov_b32_e32 v31, v8
	v_mov_b32_e32 v8, v7
	v_mov_b32_e32 v30, v6
	v_cndmask_b32_e64 v11, v11, -v11, s[6:7]
	s_waitcnt lgkmcnt(0)
	v_pk_mul_f32 v[6:7], v[8:9], v[12:13]
	v_lshlrev_b32_e32 v12, 16, v41
	v_and_b32_e32 v13, 0xffff0000, v41
	v_cndmask_b32_e64 v10, v10, -v10, s[6:7]
	v_pk_mul_f32 v[12:13], v[42:43], v[12:13] op_sel_hi:[0,1]
	v_pk_fma_f32 v[10:11], v[38:39], v[46:47], v[10:11]
	ds_bpermute_b32 v38, v153, v12
	ds_bpermute_b32 v39, v153, v13
	v_cvt_pk_bf16_f32 v139, v2, v3
	v_lshlrev_b32_e32 v2, 16, v14
	v_and_b32_e32 v3, 0xffff0000, v14
	v_cndmask_b32_e64 v7, v7, -v7, s[6:7]
	v_cndmask_b32_e64 v6, v6, -v6, s[6:7]
	v_pk_mul_f32 v[2:3], v[42:43], v[2:3] op_sel_hi:[0,1]
	v_pk_fma_f32 v[4:5], v[4:5], v[30:31], v[6:7]
	ds_bpermute_b32 v6, v153, v2
	ds_bpermute_b32 v7, v153, v3
	v_cvt_pk_bf16_f32 v137, v4, v5
	s_waitcnt lgkmcnt(2)
	v_pk_mul_f32 v[4:5], v[8:9], v[38:39]
	v_lshlrev_b32_e32 v8, 16, v15
	v_and_b32_e32 v9, 0xffff0000, v15
	v_cndmask_b32_e64 v5, v5, -v5, s[6:7]
	v_cndmask_b32_e64 v4, v4, -v4, s[6:7]
	v_pk_mul_f32 v[8:9], v[42:43], v[8:9] op_sel_hi:[0,1]
	v_pk_fma_f32 v[4:5], v[30:31], v[12:13], v[4:5]
	v_cvt_pk_bf16_f32 v140, v10, v11
	ds_bpermute_b32 v10, v153, v8
	ds_bpermute_b32 v11, v153, v9
	v_cvt_pk_bf16_f32 v141, v4, v5
	s_waitcnt vmcnt(2)
	v_mov_b32_e32 v5, v24
	v_mov_b32_e32 v24, v23
	s_waitcnt lgkmcnt(2)
	v_pk_mul_f32 v[6:7], v[24:25], v[6:7]
	v_mov_b32_e32 v4, v22
	v_cndmask_b32_e64 v7, v7, -v7, s[6:7]
	v_cndmask_b32_e64 v6, v6, -v6, s[6:7]
	v_pk_fma_f32 v[2:3], v[2:3], v[4:5], v[6:7]
	v_mov_b32_e32 v5, v20
	v_mov_b32_e32 v20, v19
	s_waitcnt lgkmcnt(0)
	v_pk_mul_f32 v[6:7], v[20:21], v[10:11]
	v_lshlrev_b32_e32 v10, 16, v16
	v_and_b32_e32 v11, 0xffff0000, v16
	v_pk_mul_f32 v[10:11], v[42:43], v[10:11] op_sel_hi:[0,1]
	ds_bpermute_b32 v12, v153, v10
	ds_bpermute_b32 v13, v153, v11
	v_mov_b32_e32 v4, v18
	v_cndmask_b32_e64 v7, v7, -v7, s[6:7]
	v_cndmask_b32_e64 v6, v6, -v6, s[6:7]
	v_pk_fma_f32 v[4:5], v[8:9], v[4:5], v[6:7]
	v_cvt_pk_bf16_f32 v142, v2, v3
	v_cvt_pk_bf16_f32 v143, v4, v5
	s_waitcnt vmcnt(0)
	v_mov_b32_e32 v7, v34
	v_mov_b32_e32 v34, v33
	s_waitcnt lgkmcnt(0)
	v_pk_mul_f32 v[8:9], v[34:35], v[12:13]
	v_lshlrev_b32_e32 v12, 16, v17
	v_and_b32_e32 v13, 0xffff0000, v17
	v_pk_mul_f32 v[12:13], v[42:43], v[12:13] op_sel_hi:[0,1]
	ds_bpermute_b32 v14, v153, v12
	ds_bpermute_b32 v15, v153, v13
	v_mov_b32_e32 v6, v32
	v_cndmask_b32_e64 v9, v9, -v9, s[6:7]
	v_cndmask_b32_e64 v8, v8, -v8, s[6:7]
	v_lshl_add_u64 v[4:5], s[24:25], 0, v[162:163]
	v_pk_fma_f32 v[6:7], v[10:11], v[6:7], v[8:9]
	v_mov_b32_e32 v9, v28
	v_mov_b32_e32 v28, v27
	v_lshl_add_u64 v[2:3], s[26:27], 0, v[160:161]
	v_lshl_add_u64 v[4:5], v[4:5], 0, v[164:165]
	s_waitcnt lgkmcnt(0)
	v_pk_mul_f32 v[10:11], v[28:29], v[14:15]
	v_cndmask_b32_e64 v3, v3, v5, s[12:13]
	v_cndmask_b32_e64 v2, v2, v4, s[12:13]
	v_lshl_add_u64 v[4:5], s[24:25], 0, v[168:169]
	v_mov_b32_e32 v8, v26
	v_cndmask_b32_e64 v11, v11, -v11, s[6:7]
	v_cndmask_b32_e64 v10, v10, -v10, s[6:7]
	v_cvt_pk_bf16_f32 v144, v6, v7
	v_lshl_add_u64 v[4:5], v[4:5], 0, v[170:171]
	v_lshl_add_u64 v[6:7], s[26:27], 0, v[166:167]
	v_pk_fma_f32 v[8:9], v[12:13], v[8:9], v[10:11]
	v_cndmask_b32_e64 v5, v7, v5, s[10:11]
	v_cndmask_b32_e64 v4, v6, v4, s[10:11]
	v_lshl_add_u64 v[6:7], s[24:25], 0, v[174:175]
	s_mov_b32 s1, m0
	s_mov_b32 m0, s60
	s_nop 0
	global_load_lds_dwordx4 v[2:3], off
	s_mov_b32 m0, s1
	v_cvt_pk_bf16_f32 v145, v8, v9
	v_lshl_add_u64 v[6:7], v[6:7], 0, v[176:177]
	v_lshl_add_u64 v[8:9], s[26:27], 0, v[172:173]
	s_mov_b32 s1, m0
	s_mov_b32 m0, s40
	s_nop 0
	global_load_lds_dwordx4 v[4:5], off
	s_mov_b32 m0, s1
	v_cndmask_b32_e64 v7, v9, v7, s[8:9]
	v_cndmask_b32_e64 v6, v8, v6, s[8:9]
	s_mov_b32 s1, m0
	s_mov_b32 m0, s41
	s_nop 0
	global_load_lds_dwordx4 v[6:7], off
	s_mov_b32 m0, s1
	v_lshl_add_u64 v[8:9], v[2:3], 0, s[92:93]
	s_add_i32 s1, s60, 0x5800
	s_mov_b32 s22, m0
	s_mov_b32 m0, s1
	s_nop 0
	global_load_lds_dwordx4 v[8:9], off
	s_mov_b32 m0, s22
	v_lshl_add_u64 v[8:9], v[4:5], 0, s[88:89]
	s_add_i32 s1, s40, 0x5800
	s_mov_b32 s22, m0
	s_mov_b32 m0, s1
	s_nop 0
	global_load_lds_dwordx4 v[8:9], off
	s_mov_b32 m0, s22
; __device__ __forceinline__ void attn_unit(LAS unsigned char* lds, const GAS bf16_t* __restrict__ QR, const GAS float* __restrict__ ssq, const GAS float* __restrict__ RT, const GAS bf16_t* __restrict__ K, const GAS bf16_t* __restrict__ Vt, GAS bf16_t* __restrict__ A2, int b, int h, int qb, int tid, i ...
;     ...
;     f32x16 oA0, oA1, oB0, oB1;
; #pragma unroll
;     for (int i = 0; i < 16; ++i) { oA0[i] = 0.f; oA1[i] = 0.f; oB0[i] = 0.f; oB1[i] = 0.f; }
;     float mA = -1e30f, mB = -1e30f, lA = 0.f, lB = 0.f;
;     constexpr int NT_ = KVLEN / 64;
;     AT_ISSUE(0, 0); AT_ISSUE(1, 1);
;     int slot = 0, nslot = 2;
; #pragma unroll 1
;     for (int t = 0; t < NT_; ++t) {
;         if (t + 1 < NT_) asm volatile("s_waitcnt vmcnt(3) lgkmcnt(0)\n\ts_barrier" ::: "memory"); else asm volatile("s_waitcnt vmcnt(0) lgkmcnt(0)\n\ts_barrier" ::: "memory");
;         if (t + 2 < NT_) AT_ISSUE(t + 2, nslot);
;         const LAS unsigned char* sb = lds + slot * AT_SLOT;
; #pragma unroll
;         for (int hh = 0; hh < 2; ++hh) {
;             const LAS unsigned char* kb = sb + (32 * hh + r32s) * AT_KROW + hi * 16;
;             f32x16 pA, pB;
; #pragma unroll
;             for (int i = 0; i < 16; ++i) { pA[i] = 0.f; pB[i] = 0.f; }
; #pragma unroll
;             for (int d0 = 0; d0 < 6; ++d0) { const bf16x8 a0 = *(const LAS bf16x8*)(kb + d0 * 32); pA = MFMA32(a0, qa[d0], pA); pB = MFMA32(a0, qc[d0], pB); }
;             u32x4 pwA0, pwA1, pwB0, pwB1;
;             float mxA, mxB; AT_LMAX(pA, mxA); AT_LMAX(pB, mxB);
;             { const float oa = __shfl_xor(mxA, 32), ob = __shfl_xor(mxB, 32); mxA = fmaxf(mxA, oa); mxB = fmaxf(mxB, ob); }
;             AT_SOFTMAX(pA, mxA, mA, lA, oA0, oA1, pwA0, pwA1);
;             AT_SOFTMAX(pB, mxB, mB, lB, oB0, oB1, pwB0, pwB1);
;             const LAS unsigned char* vb = sb + AT_VOFF + r32 * AT_VROW + hi * 16 + hh * 64;
; #pragma unroll
;             for (int ks = 0; ks < 2; ++ks) {
;                 const bf16x8 va0 = *(const LAS bf16x8*)(vb + ks * 32), va1 = *(const LAS bf16x8*)(vb + 32 * AT_VROW + ks * 32);
;                 const bf16x8 pa = __builtin_bit_cast(bf16x8, ks ? pwA1 : pwA0), pb = __builtin_bit_cast(bf16x8, ks ? pwB1 : pwB0);
;                 oA0 = MFMA32(va0, pa, oA0); oA1 = MFMA32(va1, pa, oA1); oB0 = MFMA32(va0, pb, oB0); oB1 = MFMA32(va1, pb, oB1);
;             }
;         }
	v_lshl_add_u64 v[8:9], v[6:7], 0, s[90:91]
	v_mov_b32_e32 v14, v0
	v_mov_b32_e32 v15, v0
	v_cvt_pk_bf16_f32 v108, v60, v61
	v_cvt_pk_bf16_f32 v110, v62, v63
	v_cvt_pk_bf16_f32 v112, v64, v65
	v_cvt_pk_bf16_f32 v138, v36, v37
	s_add_i32 s1, s41, 0x5800
	s_mov_b32 s22, m0
	s_mov_b32 m0, s1
	s_nop 0
	global_load_lds_dwordx4 v[8:9], off
	s_mov_b32 m0, s22
	v_lshl_add_u64 v[180:181], v[6:7], 0, s[94:95]
	v_lshl_add_u64 v[182:183], v[4:5], 0, s[96:97]
	v_lshl_add_u64 v[184:185], v[2:3], 0, s[98:99]
	v_mov_b32_e32 v1, v0
	v_mov_b32_e32 v2, v0
	v_mov_b32_e32 v3, v0
	v_mov_b32_e32 v4, v0
	v_mov_b32_e32 v5, v0
	v_mov_b32_e32 v6, v0
	v_mov_b32_e32 v7, v0
	v_mov_b32_e32 v8, v0
	v_mov_b32_e32 v9, v0
	v_mov_b32_e32 v10, v0
	v_mov_b32_e32 v11, v0
	v_mov_b32_e32 v12, v0
	v_mov_b32_e32 v13, v0
	v_mov_b64_e32 v[64:65], v[14:15]
	v_mov_b64_e32 v[48:49], v[14:15]
	v_mov_b64_e32 v[32:33], v[14:15]
	v_mov_b64_e32 v[62:63], v[12:13]
	v_mov_b64_e32 v[60:61], v[10:11]
	v_mov_b64_e32 v[58:59], v[8:9]
	v_mov_b64_e32 v[56:57], v[6:7]
	v_mov_b64_e32 v[54:55], v[4:5]
	v_mov_b64_e32 v[52:53], v[2:3]
	v_mov_b64_e32 v[50:51], v[0:1]
	v_mov_b64_e32 v[46:47], v[12:13]
	v_mov_b64_e32 v[44:45], v[10:11]
	v_mov_b64_e32 v[42:43], v[8:9]
	v_mov_b64_e32 v[40:41], v[6:7]
	v_mov_b64_e32 v[38:39], v[4:5]
	v_mov_b64_e32 v[36:37], v[2:3]
	v_mov_b64_e32 v[34:35], v[0:1]
	v_mov_b64_e32 v[30:31], v[12:13]
	v_mov_b64_e32 v[28:29], v[10:11]
	v_mov_b64_e32 v[26:27], v[8:9]
	v_mov_b64_e32 v[24:25], v[6:7]
	v_mov_b64_e32 v[22:23], v[4:5]
	v_mov_b64_e32 v[20:21], v[2:3]
	v_mov_b64_e32 v[18:19], v[0:1]
	v_mov_b64_e32 v[16:17], v[14:15]
	v_mov_b64_e32 v[14:15], v[12:13]
	v_mov_b64_e32 v[12:13], v[10:11]
	v_mov_b64_e32 v[10:11], v[8:9]
	v_mov_b64_e32 v[8:9], v[6:7]
	v_mov_b64_e32 v[6:7], v[4:5]
	v_mov_b64_e32 v[4:5], v[2:3]
	v_mov_b64_e32 v[2:3], v[0:1]
	v_add_u32_e32 v1, v154, v207
	v_add_u32_e32 v204, v155, v154
	s_mov_b32 s1, 0
	v_mov_b32_e32 v188, 0
	v_mov_b32_e32 v189, 0
	v_mov_b32_e32 v190, 0
	v_mov_b32_e32 v191, 0
	v_mov_b32_e32 v192, 0
	v_mov_b32_e32 v193, 0
	v_mov_b32_e32 v194, 0
	v_mov_b32_e32 v195, 0
	v_mov_b32_e32 v196, 0
	v_mov_b32_e32 v197, 0
	v_mov_b32_e32 v198, 0
	v_mov_b32_e32 v199, 0
	v_mov_b32_e32 v200, 0
	v_mov_b32_e32 v201, 0
	v_mov_b32_e32 v202, 0
	v_mov_b32_e32 v203, 0
	v_mov_b32_e32 v234, 0
	v_mov_b32_e32 v235, 0
	v_mov_b32_e32 v236, 0
	v_mov_b32_e32 v237, 0
	v_mov_b32_e32 v238, 0
	v_mov_b32_e32 v239, 0
	v_mov_b32_e32 v240, 0
	v_mov_b32_e32 v241, 0
	v_mov_b32_e32 v242, 0
	v_mov_b32_e32 v243, 0
	v_mov_b32_e32 v244, 0
	v_mov_b32_e32 v245, 0
	v_mov_b32_e32 v246, 0
	v_mov_b32_e32 v247, 0
	v_mov_b32_e32 v248, 0
	v_mov_b32_e32 v249, 0
	s_mov_b32 s100, 0xff800000
	s_mov_b32 s101, 0xff800000
	s_cmp_lt_i32 s0, 4
	s_cbranch_scc1 .Lat_prio_done
	s_setprio 1
.Lat_prio_done:
	s_branch .LBB0_135
.LBB0_134:
	v_exp_f32_e32 v212, v66
	v_exp_f32_e32 v213, v67
	v_exp_f32_e32 v214, v68
	v_exp_f32_e32 v215, v69
	v_exp_f32_e32 v70, v70
	v_exp_f32_e32 v71, v71
	v_exp_f32_e32 v72, v72
	v_exp_f32_e32 v73, v73
	v_exp_f32_e32 v216, v74
	v_cvt_pk_bf16_f32 v74, v212, v213
	v_add_f32_e32 v212, v213, v212
	v_add_f32_e32 v212, v214, v212
	v_add_f32_e32 v212, v215, v212
	v_exp_f32_e32 v217, v75
	v_exp_f32_e32 v218, v76
	v_cvt_pk_bf16_f32 v76, v70, v71
	v_add_f32_e32 v70, v70, v212
	v_add_f32_e32 v70, v71, v70
	v_add_f32_e32 v70, v72, v70
	v_exp_f32_e32 v219, v77
	v_add_f32_e32 v70, v73, v70
	v_exp_f32_e32 v78, v78
	v_add_f32_e32 v70, v216, v70
	v_exp_f32_e32 v79, v79
	v_add_f32_e32 v70, v217, v70
	v_exp_f32_e32 v80, v80
	v_add_f32_e32 v70, v218, v70
	v_exp_f32_e32 v81, v81
	v_add_f32_e32 v70, v219, v70
	v_add_f32_e32 v70, v78, v70
	v_add_f32_e32 v70, v79, v70
	v_add_f32_e32 v70, v80, v70
	v_add_f32_e32 v70, v81, v70
	v_add_f32_e32 v211, v211, v70
	v_exp_f32_e32 v82, v82
	v_exp_f32_e32 v83, v83
	v_exp_f32_e32 v84, v84
	v_exp_f32_e32 v85, v85
	v_cvt_pk_bf16_f32 v68, v78, v79
	v_exp_f32_e32 v86, v86
	v_cvt_pk_bf16_f32 v78, v82, v83
	v_exp_f32_e32 v87, v87
	v_add_f32_e32 v82, v83, v82
	v_exp_f32_e32 v88, v88
	v_add_f32_e32 v82, v84, v82
	v_exp_f32_e32 v89, v89
	v_add_f32_e32 v82, v85, v82
	v_exp_f32_e32 v90, v90
	v_add_f32_e32 v82, v86, v82
	v_exp_f32_e32 v91, v91
	v_add_f32_e32 v82, v87, v82
	v_exp_f32_e32 v92, v92
	v_add_f32_e32 v82, v88, v82
	v_exp_f32_e32 v93, v93
	v_add_f32_e32 v82, v89, v82
	v_exp_f32_e32 v94, v94
	v_add_f32_e32 v82, v90, v82
	v_exp_f32_e32 v95, v95
	v_add_f32_e32 v82, v91, v82
	v_exp_f32_e32 v96, v96
	v_add_f32_e32 v82, v92, v82
	v_exp_f32_e32 v97, v97
	v_add_f32_e32 v82, v93, v82
	v_add_f32_e32 v82, v94, v82
	v_add_f32_e32 v82, v95, v82
	v_add_f32_e32 v82, v96, v82
	v_cvt_pk_bf16_f32 v77, v72, v73
	v_cvt_pk_bf16_f32 v69, v80, v81
	v_cvt_pk_bf16_f32 v70, v90, v91
	v_cvt_pk_bf16_f32 v79, v84, v85
	v_cvt_pk_bf16_f32 v71, v92, v93
	v_cvt_pk_bf16_f32 v80, v86, v87
	v_cvt_pk_bf16_f32 v72, v94, v95
	v_cvt_pk_bf16_f32 v81, v88, v89
	v_add_f32_e32 v94, v97, v82
	ds_read_b128 v[82:85], v210 offset:17984
	ds_read_b128 v[86:89], v210 offset:13376
	ds_read_b128 v[90:93], v210 offset:13408
	v_cvt_pk_bf16_f32 v75, v214, v215
	s_waitcnt lgkmcnt(1)
	v_mfma_f32_32x32x16_bf16 v[18:33], v[86:89], v[78:81], v[18:33]
	v_cvt_pk_bf16_f32 v66, v216, v217
	v_cvt_pk_bf16_f32 v67, v218, v219
	v_cvt_pk_bf16_f32 v73, v96, v97
	s_add_i32 s49, s49, 1
	s_add_i32 s22, s1, 1
	s_cmp_lg_u32 s1, 2
	s_cselect_b32 s1, s22, 0
	v_mfma_f32_32x32x16_bf16 v[50:65], v[86:89], v[74:77], v[50:65]
	s_add_i32 s22, s50, 1
	s_cmp_lg_u32 s50, 2
	v_add_f32_e32 v209, v209, v94
	s_cselect_b32 s50, s22, 0
	v_lshl_add_u64 v[180:181], v[180:181], 0, s[90:91]
	v_lshl_add_u64 v[182:183], v[182:183], 0, s[88:89]
	v_lshl_add_u64 v[184:185], v[184:185], 0, s[92:93]
	v_mfma_f32_32x32x16_bf16 v[34:49], v[82:85], v[74:77], v[34:49]
	ds_read_b128 v[74:77], v210 offset:18016
	s_cmpk_lg_i32 s49, 0x84
	v_mfma_f32_32x32x16_bf16 v[2:17], v[82:85], v[78:81], v[2:17]
	s_waitcnt lgkmcnt(1)
	v_mfma_f32_32x32x16_bf16 v[50:65], v[90:93], v[66:69], v[50:65]
	s_waitcnt lgkmcnt(0)
	v_mfma_f32_32x32x16_bf16 v[34:49], v[74:77], v[66:69], v[34:49]
	v_mfma_f32_32x32x16_bf16 v[18:33], v[90:93], v[70:73], v[18:33]
	v_mfma_f32_32x32x16_bf16 v[2:17], v[74:77], v[70:73], v[2:17]
	s_cbranch_scc0 .LBB0_132

; #define LAS __attribute__((address_space(3)))
; #define MFMA32(a, b, c) __builtin_amdgcn_mfma_f32_32x32x16_bf16((a), (b), (c), 0, 0, 0)
; #define AT_LMAX(P, MX) do { MX = fmaxf(fmaxf(P[0], P[1]), fmaxf(P[2], P[3])); \
;         _Pragma("unroll") for (int i_ = 4; i_ < 16; i_ += 4) MX = fmaxf(fmaxf(MX, P[i_]), fmaxf(fmaxf(P[i_ + 1], P[i_ + 2]), P[i_ + 3])); } while (0)
; __device__ __forceinline__ void attn_unit(LAS unsigned char* lds, const GAS bf16_t* __restrict__ QR, const GAS float* __restrict__ ssq, const GAS float* __restrict__ RT, const GAS bf16_t* __restrict__ K, const GAS bf16_t* __restrict__ Vt, GAS bf16_t* __restrict__ A2, int b, int h, int qb, int tid, i ...
;     ...
;             for (int d0 = 0; d0 < 6; ++d0) { const bf16x8 a0 = *(const LAS bf16x8*)(kb + d0 * 32); pA = MFMA32(a0, qa[d0], pA); pB = MFMA32(a0, qc[d0], pB); }
;             u32x4 pwA0, pwA1, pwB0, pwB1;
;             float mxA, mxB; AT_LMAX(pA, mxA); AT_LMAX(pB, mxB);
;             { const float oa = __shfl_xor(mxA, 32), ob = __shfl_xor(mxB, 32); mxA = fmaxf(mxA, oa); mxB = fmaxf(mxB, ob); }
;             AT_SOFTMAX(pA, mxA, mA, lA, oA0, oA1, pwA0, pwA1);
;             AT_SOFTMAX(pB, mxB, mB, lB, oB0, oB1, pwB0, pwB1);
;             const LAS unsigned char* vb = sb + AT_VOFF + r32 * AT_VROW + hi * 16 + hh * 64;
; #pragma unroll
;             for (int ks = 0; ks < 2; ++ks) {
;                 const bf16x8 va0 = *(const LAS bf16x8*)(vb + ks * 32), va1 = *(const LAS bf16x8*)(vb + 32 * AT_VROW + ks * 32);
;                 const bf16x8 pa = __builtin_bit_cast(bf16x8, ks ? pwA1 : pwA0), pb = __builtin_bit_cast(bf16x8, ks ? pwB1 : pwB0);
;                 oA0 = MFMA32(va0, pa, oA0); oA1 = MFMA32(va1, pa, oA1); oB0 = MFMA32(va0, pb, oB0); oB1 = MFMA32(va1, pb, oB1);
.LBB0_143:
	s_mov_b32 s100, 0x41000000
	s_mov_b32 s101, 0
	v_exp_f32_e32 v210, v82
	v_exp_f32_e32 v213, v83
	v_exp_f32_e32 v214, v84
	v_exp_f32_e32 v215, v85
	v_exp_f32_e32 v216, v86
	v_exp_f32_e32 v217, v87
	v_exp_f32_e32 v218, v88
	v_exp_f32_e32 v219, v89
	v_cvt_pk_bf16_f32 v86, v210, v213
	v_exp_f32_e32 v90, v90
	v_add_f32_e32 v210, v213, v210
	v_exp_f32_e32 v91, v91
	v_add_f32_e32 v210, v214, v210
	v_exp_f32_e32 v92, v92
	v_add_f32_e32 v210, v215, v210
	v_exp_f32_e32 v93, v93
	v_add_f32_e32 v210, v216, v210
	v_exp_f32_e32 v213, v66
	v_exp_f32_e32 v94, v94
	v_cvt_pk_bf16_f32 v87, v214, v215
	v_add_f32_e32 v210, v217, v210
	v_exp_f32_e32 v214, v67
	v_exp_f32_e32 v95, v95
	v_add_f32_e32 v210, v218, v210
	v_exp_f32_e32 v215, v68
	v_exp_f32_e32 v96, v96
	v_cvt_pk_bf16_f32 v88, v216, v217
	v_add_f32_e32 v210, v219, v210
	v_exp_f32_e32 v216, v69
	v_exp_f32_e32 v97, v97
	v_cvt_pk_bf16_f32 v82, v90, v91
	v_add_f32_e32 v90, v90, v210
	v_exp_f32_e32 v217, v70
	v_cvt_pk_bf16_f32 v89, v218, v219
	v_add_f32_e32 v90, v91, v90
	v_exp_f32_e32 v218, v71
	v_add_f32_e32 v90, v92, v90
	v_exp_f32_e32 v219, v72
	v_add_f32_e32 v90, v93, v90
	v_exp_f32_e32 v220, v73
	v_add_f32_e32 v90, v94, v90
	v_exp_f32_e32 v221, v74
	v_add_f32_e32 v90, v95, v90
	v_exp_f32_e32 v222, v75
	v_add_f32_e32 v90, v96, v90
	v_exp_f32_e32 v223, v76
	v_add_f32_e32 v90, v97, v90
	v_exp_f32_e32 v224, v77
	v_add_f32_e32 v211, v211, v90
	v_exp_f32_e32 v225, v78
	v_exp_f32_e32 v226, v79
	v_add_u32_e32 v210, s24, v204
	v_cvt_pk_bf16_f32 v83, v92, v93
	v_exp_f32_e32 v227, v80
	v_exp_f32_e32 v228, v81
	ds_read_b128 v[74:77], v210 offset:17920
	ds_read_b128 v[78:81], v210 offset:13312
	ds_read_b128 v[90:93], v210 offset:13344
	v_cvt_pk_bf16_f32 v70, v213, v214
	v_cvt_pk_bf16_f32 v71, v215, v216
	v_cvt_pk_bf16_f32 v72, v217, v218
	v_cvt_pk_bf16_f32 v73, v219, v220
	s_waitcnt lgkmcnt(1)
	v_mfma_f32_32x32x16_bf16 v[50:65], v[78:81], v[86:89], v[50:65]
	v_cvt_pk_bf16_f32 v84, v94, v95
	v_cvt_pk_bf16_f32 v85, v96, v97
	v_cvt_pk_bf16_f32 v66, v221, v222
	v_cvt_pk_bf16_f32 v67, v223, v224
	v_cvt_pk_bf16_f32 v68, v225, v226
	v_cvt_pk_bf16_f32 v69, v227, v228
	v_mfma_f32_32x32x16_bf16 v[18:33], v[78:81], v[70:73], v[18:33]
	v_mfma_f32_32x32x16_bf16 v[2:17], v[74:77], v[70:73], v[2:17]
	v_add_f32_e32 v213, v214, v213
	v_add_f32_e32 v213, v215, v213
	v_add_f32_e32 v213, v216, v213
	v_add_f32_e32 v213, v217, v213
	v_add_f32_e32 v213, v218, v213
	v_add_f32_e32 v213, v219, v213
	v_add_f32_e32 v213, v220, v213
	v_add_f32_e32 v213, v221, v213
	v_add_f32_e32 v213, v222, v213
	v_add_f32_e32 v213, v223, v213
	v_add_f32_e32 v213, v224, v213
	v_add_f32_e32 v213, v225, v213
	v_add_f32_e32 v213, v226, v213
	v_add_f32_e32 v213, v227, v213
	v_add_f32_e32 v213, v228, v213
	v_add_f32_e32 v209, v209, v213
	ds_read_b128 v[70:73], v210 offset:17952
	v_mfma_f32_32x32x16_bf16 v[34:49], v[74:77], v[86:89], v[34:49]
	s_waitcnt lgkmcnt(1)
	v_mfma_f32_32x32x16_bf16 v[50:65], v[90:93], v[82:85], v[50:65]
	s_waitcnt lgkmcnt(0)
	v_mfma_f32_32x32x16_bf16 v[34:49], v[70:73], v[82:85], v[34:49]
	ds_read_b128 v[82:85], v212 offset:6656
	ds_read_b128 v[230:233], v212 offset:6688
	ds_read_b128 v[214:217], v212 offset:6720
	ds_read_b128 v[218:221], v212 offset:6752
	ds_read_b128 v[222:225], v212 offset:6784
	ds_read_b128 v[226:229], v212 offset:6816
	v_mfma_f32_32x32x16_bf16 v[18:33], v[90:93], v[66:69], v[18:33]
	v_mfma_f32_32x32x16_bf16 v[2:17], v[70:73], v[66:69], v[2:17]
	s_waitcnt lgkmcnt(5)
	v_mfma_f32_32x32x16_bf16 v[66:81], v[82:85], v[98:101], v[188:203]
	s_waitcnt lgkmcnt(4)
	v_mfma_f32_32x32x16_bf16 v[66:81], v[230:233], v[102:105], v[66:81]
	s_waitcnt lgkmcnt(3)
	v_mfma_f32_32x32x16_bf16 v[66:81], v[214:217], v[106:109], v[66:81]
	s_waitcnt lgkmcnt(2)
	v_mfma_f32_32x32x16_bf16 v[66:81], v[218:221], v[110:113], v[66:81]
	s_waitcnt lgkmcnt(1)
	v_mfma_f32_32x32x16_bf16 v[66:81], v[222:225], v[134:137], v[66:81]
	s_waitcnt lgkmcnt(0)
	v_mfma_f32_32x32x16_bf16 v[66:81], v[226:229], v[114:117], v[66:81]
	v_mfma_f32_32x32x16_bf16 v[82:97], v[82:85], v[118:121], v[234:249]
	v_mfma_f32_32x32x16_bf16 v[82:97], v[230:233], v[122:125], v[82:97]
	v_mfma_f32_32x32x16_bf16 v[82:97], v[214:217], v[126:129], v[82:97]
	v_mfma_f32_32x32x16_bf16 v[82:97], v[218:221], v[130:133], v[82:97]
	v_mfma_f32_32x32x16_bf16 v[82:97], v[222:225], v[138:141], v[82:97]
	v_mfma_f32_32x32x16_bf16 v[82:97], v[226:229], v[142:145], v[82:97]
	s_nop 5
	v_max_f32_e32 v250, v68, v69
	v_max3_f32 v179, v66, v67, v250
	v_max3_f32 v250, v71, v72, v73
	v_max3_f32 v251, v75, v76, v77
	v_max3_f32 v179, v179, v70, v250
	v_max3_f32 v252, v79, v80, v81
	v_max3_f32 v179, v179, v74, v251
	v_max_f32_e32 v212, v84, v85
	v_max3_f32 v212, v82, v83, v212
	v_max3_f32 v230, v87, v88, v89
	v_max3_f32 v212, v212, v86, v230
	v_max3_f32 v230, v91, v92, v93
	v_max3_f32 v212, v212, v90, v230
	v_max3_f32 v230, v95, v96, v97
	v_max3_f32 v212, v212, v94, v230
	v_max3_f32 v230, v179, v78, v252
	ds_bpermute_b32 v231, v153, v230
	ds_bpermute_b32 v179, v153, v212
	s_waitcnt lgkmcnt(1)
	v_max_f32_e32 v230, v230, v231
	v_cmp_lt_f32_e32 vcc, s100, v230
	s_cbranch_vccz .LBB0_145
	v_max_f32_e32 v231, s101, v230
	v_max_f32_e32 v230, 0, v231
	v_exp_f32_e64 v230, -v230
	v_sub_f32_e32 v188, v188, v231
	v_sub_f32_e32 v189, v189, v231
	v_sub_f32_e32 v190, v190, v231
	v_sub_f32_e32 v191, v191, v231
	v_sub_f32_e32 v192, v192, v231
	v_sub_f32_e32 v193, v193, v231
	v_sub_f32_e32 v194, v194, v231
	v_sub_f32_e32 v195, v195, v231
	v_sub_f32_e32 v196, v196, v231
	v_sub_f32_e32 v197, v197, v231
	v_sub_f32_e32 v198, v198, v231
	v_sub_f32_e32 v199, v199, v231
	v_sub_f32_e32 v200, v200, v231
	v_sub_f32_e32 v201, v201, v231
	v_sub_f32_e32 v202, v202, v231
	v_sub_f32_e32 v203, v203, v231
	v_sub_f32_e32 v66, v66, v231
	v_sub_f32_e32 v67, v67, v231
	v_sub_f32_e32 v68, v68, v231
	v_sub_f32_e32 v69, v69, v231
	v_sub_f32_e32 v70, v70, v231
	v_sub_f32_e32 v71, v71, v231
	v_sub_f32_e32 v72, v72, v231
	v_sub_f32_e32 v73, v73, v231
	v_sub_f32_e32 v74, v74, v231
	v_sub_f32_e32 v75, v75, v231
	v_sub_f32_e32 v76, v76, v231
	v_sub_f32_e32 v77, v77, v231
	v_sub_f32_e32 v78, v78, v231
	v_sub_f32_e32 v79, v79, v231
	v_sub_f32_e32 v80, v80, v231
	v_sub_f32_e32 v81, v81, v231
	v_pk_mul_f32 v[64:65], v[64:65], v[230:231] op_sel_hi:[1,0]
	v_pk_mul_f32 v[62:63], v[62:63], v[230:231] op_sel_hi:[1,0]
	v_pk_mul_f32 v[60:61], v[60:61], v[230:231] op_sel_hi:[1,0]
	v_pk_mul_f32 v[58:59], v[58:59], v[230:231] op_sel_hi:[1,0]
	v_pk_mul_f32 v[56:57], v[56:57], v[230:231] op_sel_hi:[1,0]
	v_pk_mul_f32 v[54:55], v[54:55], v[230:231] op_sel_hi:[1,0]
	v_pk_mul_f32 v[52:53], v[52:53], v[230:231] op_sel_hi:[1,0]
	v_pk_mul_f32 v[50:51], v[50:51], v[230:231] op_sel_hi:[1,0]
	v_pk_mul_f32 v[48:49], v[48:49], v[230:231] op_sel_hi:[1,0]
	v_pk_mul_f32 v[46:47], v[46:47], v[230:231] op_sel_hi:[1,0]
	v_pk_mul_f32 v[44:45], v[44:45], v[230:231] op_sel_hi:[1,0]
	v_pk_mul_f32 v[42:43], v[42:43], v[230:231] op_sel_hi:[1,0]
	v_pk_mul_f32 v[40:41], v[40:41], v[230:231] op_sel_hi:[1,0]
	v_pk_mul_f32 v[38:39], v[38:39], v[230:231] op_sel_hi:[1,0]
	v_pk_mul_f32 v[36:37], v[36:37], v[230:231] op_sel_hi:[1,0]
	v_pk_mul_f32 v[34:35], v[34:35], v[230:231] op_sel_hi:[1,0]
	v_mul_f32_e32 v211, v211, v230
